# P9-final-norm-weights-before-exchange
# baseline (speedup 1.0000x reference)
;     __device__ __forceinline__ void run(const pg8::Unit& u, LAS unsigned char* lds, int wid, int lane) const {
;     ...
;         asm volatile("s_waitcnt vmcnt(0)" ::: "memory");
;         if (lane == 0) __hip_atomic_fetch_add(cnt + 64 * u.pm, 1u, __ATOMIC_RELAXED, __HIP_MEMORY_SCOPE_AGENT);
;     __device__ __forceinline__ void fused(f32x4 (&acc)[2][2][4][2], const pg8::Unit& u, int wr, int wc, int fr, int fq, LAS unsigned char* lds, int wid, int lane) const {
;     ...
;         for (int bj = 0; bj < 2; ++bj) { const int col = col0 + bj * 128; const f32x4 w0 = *(const f32x4*)(fw + col), w1 = *(const f32x4*)(fw + col + 4);
.LBB0_947:
	s_or_b64 exec, exec, s[4:5]
	s_waitcnt vmcnt(0)
	v_lshlrev_b64 v[188:189], 2, v[160:161]
	v_lshl_add_u64 v[188:189], s[8:9], 0, v[188:189]
	global_load_dwordx4 v[192:195], v[188:189], off
	global_load_dwordx4 v[196:199], v[188:189], off offset:16
	global_load_dwordx4 v[200:203], v[188:189], off offset:512
	global_load_dwordx4 v[204:207], v[188:189], off offset:528
	s_add_u32 s12, s6, 0x8000
	s_addc_u32 s13, s7, 0
	v_cmp_eq_u32_e32 vcc, 0, v166
	s_and_saveexec_b64 s[4:5], vcc
	s_cbranch_execz .LBB0_950
	s_mov_b64 s[6:7], exec
	v_mbcnt_lo_u32_b32 v3, s6, 0
	v_mbcnt_hi_u32_b32 v3, s7, v3
	v_cmp_eq_u32_e32 vcc, 0, v3
	s_and_b64 s[16:17], exec, vcc
	s_mov_b64 exec, s[16:17]
	s_cbranch_execz .LBB0_950
	s_lshl_b32 s16, s19, 6
	s_ashr_i32 s17, s16, 31
	s_lshl_b64 s[16:17], s[16:17], 2
	s_add_u32 s16, s12, s16
	s_addc_u32 s17, s13, s17
	s_bcnt1_i32_b64 s6, s[6:7]
	v_mov_b32_e32 v3, 0
	v_mov_b32_e32 v4, s6
	global_atomic_add v3, v4, s[16:17]

; #define LAS __attribute__((address_space(3)))
;     __device__ __forceinline__ void fused(f32x4 (&acc)[2][2][4][2], const pg8::Unit& u, int wr, int wc, int fr, int fq, LAS unsigned char* lds, int wid, int lane) const {
;     ...
;         const LAS float* S = (const LAS float*)(lds + 4096);
; #pragma unroll
;         for (int bj = 0; bj < 2; ++bj) { const int col = col0 + bj * 128; const f32x4 w0 = *(const f32x4*)(fw + col), w1 = *(const f32x4*)(fw + col + 4);
; #pragma unroll
;             for (int ai = 0; ai < 2; ++ai)
; #pragma unroll
;                 for (int m = 0; m < 4; ++m) { const int r = ai * 128 + wr * 64 + m * 16 + fr; const float rstd = S[r]; const size_t off = (size_t)(u.pm * 256 + r) * DM + col;
;                     __builtin_nontemporal_store(acc[ai][bj][m][0] * rstd * w0, (f32x4*)(out + off)); __builtin_nontemporal_store(acc[ai][bj][m][1] * rstd * w1, (f32x4*)(out + off + 4)); } }
.LBB0_958:
	s_or_b64 exec, exec, s[4:5]
	v_lshlrev_b64 v[50:51], 2, v[160:161]
	s_waitcnt lgkmcnt(0)
	s_barrier
	v_lshl_add_u64 v[48:49], s[8:9], 0, v[50:51]
	v_mov_b64_e32 v[4:5], v[192:193]
	v_mov_b64_e32 v[6:7], v[194:195]
	v_mov_b64_e32 v[0:1], v[196:197]
	v_mov_b64_e32 v[2:3], v[198:199]
	v_lshl_add_u32 v54, v164, 2, 0
	v_add_u32_e32 v55, 0x1000, v54
	v_add_u32_e32 v52, s14, v164
	ds_read_b32 v134, v54 offset:4096
	ds_read_b32 v54, v54 offset:4800
	ds_read2_b32 v[160:161], v55 offset1:16
	ds_read2_b32 v[162:163], v55 offset0:16 offset1:32
	ds_read2_b32 v[164:165], v55 offset0:32 offset1:48
	ds_read2_b32 v[166:167], v55 offset0:48 offset1:128
	v_add_u32_e32 v128, 16, v52
	v_add_u32_e32 v130, 32, v52
	v_ashrrev_i32_e32 v53, 31, v52
	v_add_u32_e32 v132, 48, v52
	v_ashrrev_i32_e32 v129, 31, v128
	v_ashrrev_i32_e32 v131, 31, v130
	v_lshlrev_b64 v[136:137], 12, v[52:53]
	v_ashrrev_i32_e32 v133, 31, v132
	v_lshlrev_b64 v[128:129], 12, v[128:129]
	v_lshlrev_b64 v[130:131], 12, v[130:131]
	v_lshl_add_u64 v[136:137], s[10:11], 0, v[136:137]
	v_lshlrev_b64 v[132:133], 12, v[132:133]
	v_lshl_add_u64 v[128:129], s[10:11], 0, v[128:129]
	v_lshl_add_u64 v[130:131], s[10:11], 0, v[130:131]
	v_lshl_add_u64 v[168:169], v[136:137], 0, v[50:51]
	v_lshl_add_u64 v[132:133], s[10:11], 0, v[132:133]
	v_lshl_add_u64 v[170:171], v[128:129], 0, v[50:51]
	v_lshl_add_u64 v[172:173], v[130:131], 0, v[50:51]
	s_waitcnt lgkmcnt(5)
	v_pk_mul_f32 v[128:129], v[154:155], v[134:135] op_sel_hi:[1,0]
	v_pk_mul_f32 v[130:131], v[152:153], v[134:135] op_sel_hi:[1,0]
	s_waitcnt lgkmcnt(3)
	v_mov_b32_e32 v136, v161
	s_waitcnt lgkmcnt(2)
	v_mov_b32_e32 v138, v163
	s_waitcnt lgkmcnt(1)
	v_mov_b32_e32 v140, v165
	s_waitcnt lgkmcnt(0)
	v_mov_b32_e32 v152, v167
	v_lshl_add_u64 v[174:175], v[132:133], 0, v[50:51]
	v_pk_mul_f32 v[132:133], v[158:159], v[134:135] op_sel_hi:[1,0]
	v_pk_mul_f32 v[134:135], v[156:157], v[134:135] op_sel_hi:[1,0]
	v_pk_mul_f32 v[146:147], v[146:147], v[136:137] op_sel_hi:[1,0]
	v_pk_mul_f32 v[144:145], v[144:145], v[136:137] op_sel_hi:[1,0]
	v_pk_mul_f32 v[150:151], v[150:151], v[136:137] op_sel_hi:[1,0]
	v_pk_mul_f32 v[136:137], v[148:149], v[136:137] op_sel_hi:[1,0]
	v_pk_mul_f32 v[148:149], v[114:115], v[138:139] op_sel_hi:[1,0]
	v_pk_mul_f32 v[154:155], v[112:113], v[138:139] op_sel_hi:[1,0]
	v_pk_mul_f32 v[156:157], v[118:119], v[138:139] op_sel_hi:[1,0]
	v_pk_mul_f32 v[138:139], v[116:117], v[138:139] op_sel_hi:[1,0]
	v_pk_mul_f32 v[158:159], v[98:99], v[140:141] op_sel_hi:[1,0]
	v_pk_mul_f32 v[176:177], v[96:97], v[140:141] op_sel_hi:[1,0]
	v_pk_mul_f32 v[178:179], v[102:103], v[140:141] op_sel_hi:[1,0]
	v_pk_mul_f32 v[140:141], v[100:101], v[140:141] op_sel_hi:[1,0]
	v_pk_mul_f32 v[180:181], v[86:87], v[152:153] op_sel_hi:[1,0]
	v_pk_mul_f32 v[182:183], v[84:85], v[152:153] op_sel_hi:[1,0]
	v_add_u32_e32 v142, 0x80, v52
	v_ashrrev_i32_e32 v143, 31, v142
	v_pk_mul_f32 v[80:81], v[80:81], v[152:153] op_sel_hi:[1,0]
	v_pk_mul_f32 v[12:13], v[12:13], v[54:55] op_sel_hi:[1,0]
	v_pk_mul_f32 v[14:15], v[14:15], v[54:55] op_sel_hi:[1,0]
	s_waitcnt vmcnt(1)
	v_pk_mul_f32 v[86:87], v[6:7], v[130:131]
	v_pk_mul_f32 v[84:85], v[4:5], v[128:129]
	s_waitcnt vmcnt(0)
	v_pk_mul_f32 v[98:99], v[2:3], v[134:135]
	v_pk_mul_f32 v[96:97], v[0:1], v[132:133]
	v_pk_mul_f32 v[102:103], v[6:7], v[144:145]
	v_pk_mul_f32 v[100:101], v[4:5], v[146:147]
	v_pk_mul_f32 v[114:115], v[2:3], v[136:137]
	v_pk_mul_f32 v[112:113], v[0:1], v[150:151]
	v_pk_mul_f32 v[118:119], v[6:7], v[154:155]
	v_pk_mul_f32 v[116:117], v[4:5], v[148:149]
	v_pk_mul_f32 v[130:131], v[2:3], v[138:139]
	v_pk_mul_f32 v[128:129], v[0:1], v[156:157]
	v_pk_mul_f32 v[134:135], v[6:7], v[176:177]
	v_pk_mul_f32 v[132:133], v[4:5], v[158:159]
	v_pk_mul_f32 v[138:139], v[2:3], v[140:141]
	v_pk_mul_f32 v[136:137], v[0:1], v[178:179]
	global_store_dwordx4 v[168:169], v[84:87], off nt
	global_store_dwordx4 v[168:169], v[96:99], off offset:16 nt
	global_store_dwordx4 v[170:171], v[100:103], off nt
	global_store_dwordx4 v[170:171], v[112:115], off offset:16 nt
	global_store_dwordx4 v[172:173], v[116:119], off nt
	global_store_dwordx4 v[172:173], v[128:131], off offset:16 nt
	global_store_dwordx4 v[174:175], v[132:135], off nt
	global_store_dwordx4 v[174:175], v[136:139], off offset:16 nt
	ds_read2_b32 v[96:97], v55 offset0:128 offset1:144
	v_lshlrev_b64 v[84:85], 12, v[142:143]
	v_pk_mul_f32 v[86:87], v[82:83], v[152:153] op_sel_hi:[1,0]
	v_lshl_add_u64 v[84:85], s[10:11], 0, v[84:85]
	v_pk_mul_f32 v[82:83], v[2:3], v[80:81]
	v_pk_mul_f32 v[80:81], v[0:1], v[86:87]
	v_add_u32_e32 v86, 0x90, v52
	s_waitcnt lgkmcnt(0)
	v_mov_b32_e32 v98, v97
	v_lshl_add_u64 v[84:85], v[84:85], 0, v[50:51]
	v_ashrrev_i32_e32 v87, 31, v86
	v_pk_mul_f32 v[66:67], v[66:67], v[98:99] op_sel_hi:[1,0]
	global_store_dwordx4 v[84:85], v[80:83], off offset:16 nt
	v_pk_mul_f32 v[70:71], v[70:71], v[98:99] op_sel_hi:[1,0]
	v_pk_mul_f32 v[68:69], v[68:69], v[98:99] op_sel_hi:[1,0]
	v_pk_mul_f32 v[82:83], v[6:7], v[66:67]
	v_lshlrev_b64 v[66:67], 12, v[86:87]
	v_lshl_add_u64 v[66:67], s[10:11], 0, v[66:67]
	v_pk_mul_f32 v[80:81], v[4:5], v[70:71]
	v_lshl_add_u64 v[70:71], v[66:67], 0, v[50:51]
	global_store_dwordx4 v[70:71], v[80:83], off nt
	ds_read2_b32 v[80:81], v55 offset0:144 offset1:160
	v_pk_mul_f32 v[64:65], v[64:65], v[98:99] op_sel_hi:[1,0]
	v_pk_mul_f32 v[140:141], v[6:7], v[182:183]
	v_pk_mul_f32 v[66:67], v[2:3], v[64:65]
	v_pk_mul_f32 v[64:65], v[0:1], v[68:69]
	global_store_dwordx4 v[70:71], v[64:67], off offset:16 nt
	v_pk_mul_f32 v[138:139], v[4:5], v[180:181]
	global_store_dwordx4 v[84:85], v[138:141], off nt
	v_add_u32_e32 v64, 0xa0, v52
	v_ashrrev_i32_e32 v65, 31, v64
	s_waitcnt lgkmcnt(0)
;     __device__ __forceinline__ void fused(f32x4 (&acc)[2][2][4][2], const pg8::Unit& u, int wr, int wc, int fr, int fq, LAS unsigned char* lds, int wid, int lane) const {
;     ...
;         for (int bj = 0; bj < 2; ++bj) { const int col = col0 + bj * 128; const f32x4 w0 = *(const f32x4*)(fw + col), w1 = *(const f32x4*)(fw + col + 4);
; #pragma unroll
;             for (int ai = 0; ai < 2; ++ai)
; #pragma unroll
;                 for (int m = 0; m < 4; ++m) { const int r = ai * 128 + wr * 64 + m * 16 + fr; const float rstd = S[r]; const size_t off = (size_t)(u.pm * 256 + r) * DM + col;
;                     __builtin_nontemporal_store(acc[ai][bj][m][0] * rstd * w0, (f32x4*)(out + off)); __builtin_nontemporal_store(acc[ai][bj][m][1] * rstd * w1, (f32x4*)(out + off + 4)); } }
	v_mov_b32_e32 v66, v81
	v_lshlrev_b64 v[64:65], 12, v[64:65]
	v_lshl_add_u64 v[64:65], s[10:11], 0, v[64:65]
	v_pk_mul_f32 v[24:25], v[24:25], v[66:67] op_sel_hi:[1,0]
	v_pk_mul_f32 v[26:27], v[26:27], v[66:67] op_sel_hi:[1,0]
	v_lshl_add_u64 v[64:65], v[64:65], 0, v[50:51]
	v_pk_mul_f32 v[26:27], v[2:3], v[26:27]
	v_pk_mul_f32 v[24:25], v[0:1], v[24:25]
	global_store_dwordx4 v[64:65], v[24:27], off offset:16 nt
	v_pk_mul_f32 v[28:29], v[28:29], v[66:67] op_sel_hi:[1,0]
	v_pk_mul_f32 v[30:31], v[30:31], v[66:67] op_sel_hi:[1,0]
	v_add_u32_e32 v24, 0xb0, v52
	v_ashrrev_i32_e32 v25, 31, v24
	v_pk_mul_f32 v[30:31], v[6:7], v[30:31]
	v_pk_mul_f32 v[28:29], v[4:5], v[28:29]
	v_lshlrev_b64 v[24:25], 12, v[24:25]
	global_store_dwordx4 v[64:65], v[28:31], off nt
	v_pk_mul_f32 v[26:27], v[38:39], v[54:55] op_sel_hi:[1,0]
	v_lshl_add_u64 v[24:25], s[10:11], 0, v[24:25]
	v_pk_mul_f32 v[28:29], v[34:35], v[54:55] op_sel_hi:[1,0]
	v_pk_mul_f32 v[4:5], v[4:5], v[26:27]
	v_pk_mul_f32 v[6:7], v[6:7], v[28:29]
	v_lshl_add_u64 v[50:51], v[24:25], 0, v[50:51]
	global_store_dwordx4 v[50:51], v[4:7], off nt
	v_pk_mul_f32 v[24:25], v[126:127], v[160:161] op_sel_hi:[1,0]
	v_pk_mul_f32 v[26:27], v[122:123], v[160:161] op_sel_hi:[1,0]
	v_pk_mul_f32 v[4:5], v[36:37], v[54:55] op_sel_hi:[1,0]
	v_pk_mul_f32 v[6:7], v[32:33], v[54:55] op_sel_hi:[1,0]
	v_pk_mul_f32 v[0:1], v[0:1], v[4:5]
	v_pk_mul_f32 v[2:3], v[2:3], v[6:7]
	global_store_dwordx4 v[50:51], v[0:3], off offset:16 nt
	v_mov_b64_e32 v[4:5], v[204:205]
	v_mov_b64_e32 v[6:7], v[206:207]
	s_nop 0
	v_mov_b64_e32 v[0:1], v[200:201]
	v_mov_b64_e32 v[2:3], v[202:203]
	v_pk_mul_f32 v[28:29], v[124:125], v[160:161] op_sel_hi:[1,0]
	v_pk_mul_f32 v[30:31], v[120:121], v[160:161] op_sel_hi:[1,0]
	v_pk_mul_f32 v[32:33], v[110:111], v[162:163] op_sel_hi:[1,0]
	v_pk_mul_f32 v[34:35], v[106:107], v[162:163] op_sel_hi:[1,0]
	v_pk_mul_f32 v[36:37], v[108:109], v[162:163] op_sel_hi:[1,0]
	v_pk_mul_f32 v[38:39], v[104:105], v[162:163] op_sel_hi:[1,0]
	v_pk_mul_f32 v[48:49], v[94:95], v[164:165] op_sel_hi:[1,0]
	v_pk_mul_f32 v[22:23], v[22:23], v[66:67] op_sel_hi:[1,0]
	v_pk_mul_f32 v[20:21], v[20:21], v[66:67] op_sel_hi:[1,0]
	v_pk_mul_f32 v[18:19], v[18:19], v[66:67] op_sel_hi:[1,0]
	v_pk_mul_f32 v[16:17], v[16:17], v[66:67] op_sel_hi:[1,0]
	v_pk_mul_f32 v[26:27], v[2:3], v[26:27]
	v_pk_mul_f32 v[24:25], v[0:1], v[24:25]
	v_pk_mul_f32 v[30:31], v[6:7], v[30:31]
	v_pk_mul_f32 v[28:29], v[4:5], v[28:29]
	v_pk_mul_f32 v[34:35], v[2:3], v[34:35]
	v_pk_mul_f32 v[32:33], v[0:1], v[32:33]
	v_pk_mul_f32 v[38:39], v[6:7], v[38:39]
	v_pk_mul_f32 v[36:37], v[4:5], v[36:37]
	global_store_dwordx4 v[168:169], v[24:27], off offset:512 nt
	global_store_dwordx4 v[168:169], v[28:31], off offset:528 nt
	global_store_dwordx4 v[170:171], v[32:35], off offset:512 nt
	global_store_dwordx4 v[170:171], v[36:39], off offset:528 nt
	v_pk_mul_f32 v[24:25], v[90:91], v[164:165] op_sel_hi:[1,0]
	v_pk_mul_f32 v[20:21], v[0:1], v[20:21]
	v_pk_mul_f32 v[26:27], v[2:3], v[24:25]
	v_pk_mul_f32 v[24:25], v[0:1], v[48:49]
	global_store_dwordx4 v[172:173], v[24:27], off offset:512 nt
	v_pk_mul_f32 v[22:23], v[2:3], v[22:23]
	v_pk_mul_f32 v[16:17], v[4:5], v[16:17]
	v_pk_mul_f32 v[24:25], v[92:93], v[164:165] op_sel_hi:[1,0]
	v_pk_mul_f32 v[26:27], v[88:89], v[164:165] op_sel_hi:[1,0]
	v_pk_mul_f32 v[24:25], v[4:5], v[24:25]
	v_pk_mul_f32 v[26:27], v[6:7], v[26:27]
	global_store_dwordx4 v[172:173], v[24:27], off offset:528 nt
	v_pk_mul_f32 v[18:19], v[6:7], v[18:19]
	global_store_dwordx4 v[64:65], v[20:23], off offset:512 nt
	v_pk_mul_f32 v[24:25], v[78:79], v[166:167] op_sel_hi:[1,0]
	v_pk_mul_f32 v[26:27], v[74:75], v[166:167] op_sel_hi:[1,0]
	v_pk_mul_f32 v[24:25], v[0:1], v[24:25]
	v_pk_mul_f32 v[26:27], v[2:3], v[26:27]
	global_store_dwordx4 v[174:175], v[24:27], off offset:512 nt
	global_store_dwordx4 v[64:65], v[16:19], off offset:528 nt
	s_nop 0
	v_pk_mul_f32 v[24:25], v[76:77], v[166:167] op_sel_hi:[1,0]
	v_pk_mul_f32 v[26:27], v[72:73], v[166:167] op_sel_hi:[1,0]
	v_pk_mul_f32 v[24:25], v[4:5], v[24:25]
	v_pk_mul_f32 v[26:27], v[6:7], v[26:27]
	global_store_dwordx4 v[174:175], v[24:27], off offset:528 nt
	s_nop 1
	v_pk_mul_f32 v[24:25], v[62:63], v[96:97] op_sel_hi:[1,0]
	v_pk_mul_f32 v[26:27], v[58:59], v[96:97] op_sel_hi:[1,0]
	v_pk_mul_f32 v[24:25], v[0:1], v[24:25]
	v_pk_mul_f32 v[26:27], v[2:3], v[26:27]
	global_store_dwordx4 v[84:85], v[24:27], off offset:512 nt
	s_nop 1
	v_pk_mul_f32 v[24:25], v[60:61], v[96:97] op_sel_hi:[1,0]
	v_pk_mul_f32 v[26:27], v[56:57], v[96:97] op_sel_hi:[1,0]
	v_pk_mul_f32 v[24:25], v[4:5], v[24:25]
	v_pk_mul_f32 v[26:27], v[6:7], v[26:27]
	global_store_dwordx4 v[84:85], v[24:27], off offset:528 nt
	s_nop 1
	v_pk_mul_f32 v[24:25], v[46:47], v[80:81] op_sel_hi:[1,0]
	v_pk_mul_f32 v[26:27], v[42:43], v[80:81] op_sel_hi:[1,0]
	v_pk_mul_f32 v[24:25], v[0:1], v[24:25]
	v_pk_mul_f32 v[26:27], v[2:3], v[26:27]
	v_pk_mul_f32 v[0:1], v[0:1], v[14:15]
	v_pk_mul_f32 v[2:3], v[2:3], v[12:13]
	global_store_dwordx4 v[70:71], v[24:27], off offset:512 nt
	global_store_dwordx4 v[50:51], v[0:3], off offset:512 nt
	s_nop 0
	v_pk_mul_f32 v[24:25], v[44:45], v[80:81] op_sel_hi:[1,0]
	v_pk_mul_f32 v[26:27], v[40:41], v[80:81] op_sel_hi:[1,0]
	v_pk_mul_f32 v[2:3], v[8:9], v[54:55] op_sel_hi:[1,0]
	v_pk_mul_f32 v[0:1], v[10:11], v[54:55] op_sel_hi:[1,0]
	v_pk_mul_f32 v[26:27], v[6:7], v[26:27]
	v_pk_mul_f32 v[24:25], v[4:5], v[24:25]
	v_pk_mul_f32 v[0:1], v[4:5], v[0:1]
	v_pk_mul_f32 v[2:3], v[6:7], v[2:3]
	global_store_dwordx4 v[70:71], v[24:27], off offset:528 nt
	global_store_dwordx4 v[50:51], v[0:3], off offset:528 nt
